# v54 + de-serialised diff-attention epilogue: the eight subln-gain loads issued together and waited once, seven store-draining waits removed
# speedup vs baseline: 1.0146x; 1.0020x over previous
.LBB0_1054:
	v_rcp_f32_e32 v2, v194
	v_rcp_f32_e32 v0, v195
	v_mov_b32_e32 v161, v1
	s_add_i32 s22, s22, 1
	v_mul_f32_e32 v6, v164, v2
	v_pk_mul_f32 v[4:5], v[6:7], v[108:109] op_sel_hi:[0,1]
	v_pk_fma_f32 v[10:11], v[0:1], v[112:113], v[4:5] op_sel_hi:[0,1,1] neg_lo:[0,0,1] neg_hi:[0,0,1]
	v_pk_mul_f32 v[2:3], v[6:7], v[110:111] op_sel_hi:[0,1]
	v_mul_f32_e32 v7, v11, v11
	v_pk_fma_f32 v[8:9], v[0:1], v[114:115], v[2:3] op_sel_hi:[0,1,1] neg_lo:[0,0,1] neg_hi:[0,0,1]
	v_fmac_f32_e32 v7, v10, v10
	v_fmac_f32_e32 v7, v8, v8
	v_fmac_f32_e32 v7, v9, v9
	v_pk_mul_f32 v[2:3], v[6:7], v[102:103] op_sel_hi:[0,1]
	v_pk_mul_f32 v[4:5], v[6:7], v[100:101] op_sel_hi:[0,1]
	v_pk_fma_f32 v[12:13], v[0:1], v[106:107], v[2:3] op_sel_hi:[0,1,1] neg_lo:[0,0,1] neg_hi:[0,0,1]
	v_pk_fma_f32 v[14:15], v[0:1], v[104:105], v[4:5] op_sel_hi:[0,1,1] neg_lo:[0,0,1] neg_hi:[0,0,1]
	global_load_dwordx4 v[2:5], v[158:159], off
	v_mul_f32_e32 v16, v15, v15
	v_fmac_f32_e32 v16, v14, v14
	v_fmac_f32_e32 v16, v12, v12
	v_fmac_f32_e32 v16, v13, v13
	v_add_f32_e32 v7, v7, v16
	v_pk_mul_f32 v[18:19], v[6:7], v[92:93] op_sel_hi:[0,1]
	v_pk_fma_f32 v[18:19], v[0:1], v[96:97], v[18:19] op_sel_hi:[0,1,1] neg_lo:[0,0,1] neg_hi:[0,0,1]
	v_pk_mul_f32 v[16:17], v[6:7], v[94:95] op_sel_hi:[0,1]
	s_waitcnt vmcnt(3)
	v_mul_f32_e32 v20, v19, v19
	v_pk_fma_f32 v[16:17], v[0:1], v[98:99], v[16:17] op_sel_hi:[0,1,1] neg_lo:[0,0,1] neg_hi:[0,0,1]
	v_fmac_f32_e32 v20, v18, v18
	v_fmac_f32_e32 v20, v16, v16
	v_fmac_f32_e32 v20, v17, v17
	v_add_f32_e32 v7, v7, v20
	v_pk_mul_f32 v[22:23], v[6:7], v[84:85] op_sel_hi:[0,1]
	v_pk_fma_f32 v[22:23], v[0:1], v[88:89], v[22:23] op_sel_hi:[0,1,1] neg_lo:[0,0,1] neg_hi:[0,0,1]
	v_pk_mul_f32 v[20:21], v[6:7], v[86:87] op_sel_hi:[0,1]
	v_mul_f32_e32 v24, v23, v23
	v_pk_fma_f32 v[20:21], v[0:1], v[90:91], v[20:21] op_sel_hi:[0,1,1] neg_lo:[0,0,1] neg_hi:[0,0,1]
	v_fmac_f32_e32 v24, v22, v22
	v_fmac_f32_e32 v24, v20, v20
	v_fmac_f32_e32 v24, v21, v21
	v_add_f32_e32 v7, v7, v24
	v_pk_mul_f32 v[26:27], v[6:7], v[76:77] op_sel_hi:[0,1]
	v_pk_fma_f32 v[26:27], v[0:1], v[80:81], v[26:27] op_sel_hi:[0,1,1] neg_lo:[0,0,1] neg_hi:[0,0,1]
	v_pk_mul_f32 v[24:25], v[6:7], v[78:79] op_sel_hi:[0,1]
	v_mul_f32_e32 v28, v27, v27
	v_pk_fma_f32 v[24:25], v[0:1], v[82:83], v[24:25] op_sel_hi:[0,1,1] neg_lo:[0,0,1] neg_hi:[0,0,1]
	v_fmac_f32_e32 v28, v26, v26
	v_fmac_f32_e32 v28, v24, v24
	v_fmac_f32_e32 v28, v25, v25
	v_add_f32_e32 v7, v7, v28
	v_pk_mul_f32 v[30:31], v[6:7], v[68:69] op_sel_hi:[0,1]
	v_pk_fma_f32 v[30:31], v[0:1], v[72:73], v[30:31] op_sel_hi:[0,1,1] neg_lo:[0,0,1] neg_hi:[0,0,1]
	v_pk_mul_f32 v[28:29], v[6:7], v[70:71] op_sel_hi:[0,1]
	v_mul_f32_e32 v32, v31, v31
	v_pk_fma_f32 v[28:29], v[0:1], v[74:75], v[28:29] op_sel_hi:[0,1,1] neg_lo:[0,0,1] neg_hi:[0,0,1]
	v_fmac_f32_e32 v32, v30, v30
	v_fmac_f32_e32 v32, v28, v28
	v_fmac_f32_e32 v32, v29, v29
	s_waitcnt vmcnt(1)
	global_load_dwordx4 v[44:47], v[158:159], off offset:64
	global_load_dwordx4 v[48:51], v[158:159], off offset:128
	global_load_dwordx4 v[220:223], v[158:159], off offset:192
	global_load_dwordx4 v[228:231], v[158:159], off offset:256
	global_load_dwordx4 v[234:237], v[158:159], off offset:320
	global_load_dwordx4 v[238:241], v[158:159], off offset:384
	global_load_dwordx4 v[242:245], v[158:159], off offset:448
	v_add_f32_e32 v42, v7, v32
	v_pk_mul_f32 v[32:33], v[6:7], v[58:59] op_sel_hi:[0,1]
	v_pk_mul_f32 v[34:35], v[6:7], v[56:57] op_sel_hi:[0,1]
	v_pk_mul_f32 v[36:37], v[6:7], v[54:55] op_sel_hi:[0,1]
	v_pk_mul_f32 v[6:7], v[6:7], v[52:53] op_sel_hi:[0,1]
	v_pk_fma_f32 v[34:35], v[0:1], v[64:65], v[34:35] op_sel_hi:[0,1,1] neg_lo:[0,0,1] neg_hi:[0,0,1]
	v_pk_fma_f32 v[6:7], v[0:1], v[60:61], v[6:7] op_sel_hi:[0,1,1] neg_lo:[0,0,1] neg_hi:[0,0,1]
	v_mov_b32_e32 v40, v35
	v_mov_b32_e32 v41, v7
	v_pk_fma_f32 v[32:33], v[0:1], v[66:67], v[32:33] op_sel_hi:[0,1,1] neg_lo:[0,0,1] neg_hi:[0,0,1]
	v_pk_fma_f32 v[36:37], v[0:1], v[62:63], v[36:37] op_sel_hi:[0,1,1] neg_lo:[0,0,1] neg_hi:[0,0,1]
	v_mov_b32_e32 v38, v34
	v_mov_b32_e32 v39, v6
	v_pk_mul_f32 v[40:41], v[40:41], v[40:41]
	s_nop 0
	v_pk_fma_f32 v[38:39], v[38:39], v[38:39], v[40:41]
	v_mov_b32_e32 v40, v32
	v_mov_b32_e32 v41, v36
	v_pk_fma_f32 v[38:39], v[40:41], v[40:41], v[38:39]
	v_mov_b32_e32 v40, v33
	v_mov_b32_e32 v41, v37
	v_pk_fma_f32 v[38:39], v[40:41], v[40:41], v[38:39]
	s_nop 0
	v_add_f32_e32 v0, v42, v38
	v_add_f32_e32 v0, v0, v39
	ds_bpermute_b32 v38, v198, v0
	s_waitcnt lgkmcnt(0)
	v_add_f32_e32 v0, v0, v38
	ds_bpermute_b32 v40, v179, v0
	v_lshl_add_u64 v[38:39], s[8:9], 0, v[162:163]
	v_lshl_add_u64 v[38:39], s[12:13], 1, v[38:39]
	v_lshl_add_u64 v[38:39], v[38:39], 0, v[160:161]
	s_mov_b64 s[12:13], 0
	s_waitcnt lgkmcnt(0)
	v_add_f32_e32 v0, v0, v40
	v_fmamk_f32 v0, v0, 0x3c000000, v227
	v_rsq_f32_e32 v0, v0
	s_nop 0
	v_mul_f32_e32 v0, v165, v0
	v_mul_f32_e32 v10, v10, v0
	s_waitcnt vmcnt(0)
	v_mul_f32_e32 v2, v2, v10
	v_mul_f32_e32 v10, v11, v0
	v_mul_f32_e32 v3, v3, v10
	v_cvt_pk_bf16_f32 v2, v2, v3
	v_mul_f32_e32 v3, v8, v0
	v_mul_f32_e32 v3, v4, v3
	v_mul_f32_e32 v4, v9, v0
	v_mul_f32_e32 v4, v5, v4
	v_cvt_pk_bf16_f32 v3, v3, v4
	global_store_dwordx2 v[38:39], v[2:3], off
	v_mul_f32_e32 v8, v14, v0
	v_mul_f32_e32 v9, v15, v0
	v_mul_f32_e32 v10, v12, v0
	v_mul_f32_e32 v11, v13, v0
	v_mul_f32_e32 v6, v6, v0
	v_mul_f32_e32 v7, v7, v0
	v_mul_f32_e32 v2, v44, v8
	v_mul_f32_e32 v3, v45, v9
	v_mul_f32_e32 v4, v46, v10
	v_mul_f32_e32 v5, v47, v11
	v_cvt_pk_bf16_f32 v2, v2, v3
	v_cvt_pk_bf16_f32 v3, v4, v5
	global_store_dwordx2 v[38:39], v[2:3], off offset:32
	v_mul_f32_e32 v8, v18, v0
	v_mul_f32_e32 v9, v19, v0
	v_mul_f32_e32 v10, v16, v0
	v_mul_f32_e32 v11, v17, v0
	v_mul_f32_e32 v2, v8, v48
	v_mul_f32_e32 v3, v9, v49
	v_mul_f32_e32 v4, v10, v50
	v_mul_f32_e32 v5, v11, v51
	v_cvt_pk_bf16_f32 v2, v2, v3
	v_cvt_pk_bf16_f32 v3, v4, v5
	global_store_dwordx2 v[38:39], v[2:3], off offset:64
	v_mul_f32_e32 v8, v22, v0
	v_mul_f32_e32 v9, v23, v0
	v_mul_f32_e32 v10, v20, v0
	v_mul_f32_e32 v11, v21, v0
	v_mul_f32_e32 v2, v8, v220
	v_mul_f32_e32 v3, v9, v221
	v_mul_f32_e32 v4, v10, v222
	v_mul_f32_e32 v5, v11, v223
	v_cvt_pk_bf16_f32 v2, v2, v3
	v_cvt_pk_bf16_f32 v3, v4, v5
	global_store_dwordx2 v[38:39], v[2:3], off offset:96
	v_mul_f32_e32 v8, v26, v0
	v_mul_f32_e32 v9, v27, v0
	v_mul_f32_e32 v10, v24, v0
	v_mul_f32_e32 v11, v25, v0
	v_mul_f32_e32 v2, v8, v228
	v_mul_f32_e32 v3, v9, v229
	v_mul_f32_e32 v4, v10, v230
	v_mul_f32_e32 v5, v11, v231
	v_cvt_pk_bf16_f32 v2, v2, v3
	v_cvt_pk_bf16_f32 v3, v4, v5
	global_store_dwordx2 v[38:39], v[2:3], off offset:128
	v_mul_f32_e32 v8, v30, v0
	v_mul_f32_e32 v9, v31, v0
	v_mul_f32_e32 v10, v28, v0
	v_mul_f32_e32 v11, v29, v0
	v_mul_f32_e32 v2, v8, v234
	v_mul_f32_e32 v3, v9, v235
	v_mul_f32_e32 v4, v10, v236
	v_mul_f32_e32 v5, v11, v237
	v_cvt_pk_bf16_f32 v2, v2, v3
	v_cvt_pk_bf16_f32 v3, v4, v5
	global_store_dwordx2 v[38:39], v[2:3], off offset:160
	v_mul_f32_e32 v8, v34, v0
	v_mul_f32_e32 v9, v35, v0
	v_mul_f32_e32 v10, v32, v0
	v_mul_f32_e32 v11, v33, v0
	v_mul_f32_e32 v2, v8, v238
	v_mul_f32_e32 v3, v9, v239
	v_mul_f32_e32 v4, v10, v240
	v_mul_f32_e32 v5, v11, v241
	v_cvt_pk_bf16_f32 v2, v2, v3
	v_cvt_pk_bf16_f32 v3, v4, v5
	global_store_dwordx2 v[38:39], v[2:3], off offset:192
	v_mul_f32_e32 v8, v36, v0
	v_mul_f32_e32 v0, v37, v0
	v_mul_f32_e32 v2, v6, v242
	v_mul_f32_e32 v3, v7, v243
	v_mul_f32_e32 v4, v8, v244
	v_mul_f32_e32 v0, v0, v245
	v_cvt_pk_bf16_f32 v2, v2, v3
	v_cvt_pk_bf16_f32 v3, v4, v0
	global_store_dwordx2 v[38:39], v[2:3], off offset:224
